# non-temporal hint on the f32 k/v cache output stores (P1) and y stores (P6)
# speedup vs baseline: 1.0057x; 1.0013x over previous
.LBB0_171:
	v_cmp_ne_u64_e32 vcc, 0, v[170:171]
	v_cvt_pk_bf16_f32 v174, v124, v125
	v_cvt_pk_bf16_f32 v175, v126, v127
	v_cvt_pk_bf16_f32 v176, v120, v121
	v_cvt_pk_bf16_f32 v177, v122, v123
	v_lshl_add_u64 v[172:173], v[138:139], 1, v[172:173]
	v_lshl_add_u64 v[170:171], v[138:139], 2, v[170:171]
	global_store_dwordx4 v[172:173], v[174:177], off
	s_and_saveexec_b64 s[8:9], vcc
	s_cbranch_execz .LBB0_173
	global_store_dwordx4 v[170:171], v[124:127], off nt
	global_store_dwordx4 v[170:171], v[120:123], off offset:16 nt
.LBB0_173:
	s_or_b64 exec, exec, s[8:9]
	s_nop 0
	v_cvt_pk_bf16_f32 v120, v116, v117
	v_cvt_pk_bf16_f32 v121, v118, v119
	v_cvt_pk_bf16_f32 v122, v112, v113
	v_cvt_pk_bf16_f32 v123, v114, v115
	global_store_dwordx4 v[172:173], v[120:123], off offset:64
	s_and_saveexec_b64 s[8:9], vcc
	s_cbranch_execz .LBB0_175
	global_store_dwordx4 v[170:171], v[116:119], off offset:128 nt
	global_store_dwordx4 v[170:171], v[112:115], off offset:144 nt

.LBB0_197:
	v_cmp_ne_u64_e32 vcc, 0, v[112:113]
	v_cvt_pk_bf16_f32 v118, v108, v109
	v_cvt_pk_bf16_f32 v119, v110, v111
	v_cvt_pk_bf16_f32 v120, v104, v105
	v_cvt_pk_bf16_f32 v121, v106, v107
	v_lshl_add_u64 v[114:115], v[138:139], 1, v[116:117]
	v_lshl_add_u64 v[112:113], v[138:139], 2, v[112:113]
	global_store_dwordx4 v[114:115], v[118:121], off
	s_and_saveexec_b64 s[20:21], vcc
	s_cbranch_execz .LBB0_199
	global_store_dwordx4 v[112:113], v[108:111], off nt
	global_store_dwordx4 v[112:113], v[104:107], off offset:16 nt
.LBB0_199:
	s_or_b64 exec, exec, s[20:21]
	s_nop 0
	v_cvt_pk_bf16_f32 v104, v100, v101
	v_cvt_pk_bf16_f32 v105, v102, v103
	v_cvt_pk_bf16_f32 v106, v96, v97
	v_cvt_pk_bf16_f32 v107, v98, v99
	global_store_dwordx4 v[114:115], v[104:107], off offset:64
	s_and_saveexec_b64 s[20:21], vcc
	s_cbranch_execz .LBB0_201
	global_store_dwordx4 v[112:113], v[100:103], off offset:128 nt
	global_store_dwordx4 v[112:113], v[96:99], off offset:144 nt

.LBB0_223:
	v_cmp_ne_u64_e32 vcc, 0, v[96:97]
	v_cvt_pk_bf16_f32 v102, v92, v93
	v_cvt_pk_bf16_f32 v103, v94, v95
	v_cvt_pk_bf16_f32 v104, v88, v89
	v_cvt_pk_bf16_f32 v105, v90, v91
	v_lshl_add_u64 v[98:99], v[138:139], 1, v[100:101]
	v_lshl_add_u64 v[96:97], v[138:139], 2, v[96:97]
	global_store_dwordx4 v[98:99], v[102:105], off
	s_and_saveexec_b64 s[20:21], vcc
	s_cbranch_execz .LBB0_225
	global_store_dwordx4 v[96:97], v[92:95], off nt
	global_store_dwordx4 v[96:97], v[88:91], off offset:16 nt
.LBB0_225:
	s_or_b64 exec, exec, s[20:21]
	s_nop 0
	v_cvt_pk_bf16_f32 v88, v84, v85
	v_cvt_pk_bf16_f32 v89, v86, v87
	v_cvt_pk_bf16_f32 v90, v80, v81
	v_cvt_pk_bf16_f32 v91, v82, v83
	global_store_dwordx4 v[98:99], v[88:91], off offset:64
	s_and_saveexec_b64 s[20:21], vcc
	s_cbranch_execz .LBB0_227
	global_store_dwordx4 v[96:97], v[84:87], off offset:128 nt
	global_store_dwordx4 v[96:97], v[80:83], off offset:144 nt

.LBB0_249:
	v_cmp_ne_u64_e32 vcc, 0, v[80:81]
	v_cvt_pk_bf16_f32 v86, v76, v77
	v_cvt_pk_bf16_f32 v87, v78, v79
	v_cvt_pk_bf16_f32 v88, v72, v73
	v_cvt_pk_bf16_f32 v89, v74, v75
	v_lshl_add_u64 v[82:83], v[138:139], 1, v[84:85]
	v_lshl_add_u64 v[80:81], v[138:139], 2, v[80:81]
	global_store_dwordx4 v[82:83], v[86:89], off
	s_and_saveexec_b64 s[20:21], vcc
	s_cbranch_execz .LBB0_251
	global_store_dwordx4 v[80:81], v[76:79], off nt
	global_store_dwordx4 v[80:81], v[72:75], off offset:16 nt
.LBB0_251:
	s_or_b64 exec, exec, s[20:21]
	s_nop 0
	v_cvt_pk_bf16_f32 v72, v68, v69
	v_cvt_pk_bf16_f32 v73, v70, v71
	v_cvt_pk_bf16_f32 v74, v64, v65
	v_cvt_pk_bf16_f32 v75, v66, v67
	global_store_dwordx4 v[82:83], v[72:75], off offset:64
	s_and_saveexec_b64 s[20:21], vcc
	s_cbranch_execz .LBB0_253
	global_store_dwordx4 v[80:81], v[68:71], off offset:128 nt
	global_store_dwordx4 v[80:81], v[64:67], off offset:144 nt

.LBB0_275:
	v_cmp_ne_u64_e32 vcc, 0, v[64:65]
	v_cvt_pk_bf16_f32 v70, v60, v61
	v_cvt_pk_bf16_f32 v71, v62, v63
	v_cvt_pk_bf16_f32 v72, v56, v57
	v_cvt_pk_bf16_f32 v73, v58, v59
	v_lshl_add_u64 v[66:67], v[138:139], 1, v[68:69]
	v_lshl_add_u64 v[64:65], v[138:139], 2, v[64:65]
	global_store_dwordx4 v[66:67], v[70:73], off
	s_and_saveexec_b64 s[20:21], vcc
	s_cbranch_execz .LBB0_277
	global_store_dwordx4 v[64:65], v[60:63], off nt
	global_store_dwordx4 v[64:65], v[56:59], off offset:16 nt
.LBB0_277:
	s_or_b64 exec, exec, s[20:21]
	s_nop 0
	v_cvt_pk_bf16_f32 v56, v52, v53
	v_cvt_pk_bf16_f32 v57, v54, v55
	v_cvt_pk_bf16_f32 v58, v48, v49
	v_cvt_pk_bf16_f32 v59, v50, v51
	global_store_dwordx4 v[66:67], v[56:59], off offset:64
	s_and_saveexec_b64 s[20:21], vcc
	s_cbranch_execz .LBB0_279
	global_store_dwordx4 v[64:65], v[52:55], off offset:128 nt
	global_store_dwordx4 v[64:65], v[48:51], off offset:144 nt

.LBB0_301:
	v_cmp_ne_u64_e32 vcc, 0, v[48:49]
	v_cvt_pk_bf16_f32 v54, v44, v45
	v_cvt_pk_bf16_f32 v55, v46, v47
	v_cvt_pk_bf16_f32 v56, v40, v41
	v_cvt_pk_bf16_f32 v57, v42, v43
	v_lshl_add_u64 v[50:51], v[138:139], 1, v[52:53]
	v_lshl_add_u64 v[48:49], v[138:139], 2, v[48:49]
	global_store_dwordx4 v[50:51], v[54:57], off
	s_and_saveexec_b64 s[20:21], vcc
	s_cbranch_execz .LBB0_303
	global_store_dwordx4 v[48:49], v[44:47], off nt
	global_store_dwordx4 v[48:49], v[40:43], off offset:16 nt
.LBB0_303:
	s_or_b64 exec, exec, s[20:21]
	s_nop 0
	v_cvt_pk_bf16_f32 v40, v36, v37
	v_cvt_pk_bf16_f32 v41, v38, v39
	v_cvt_pk_bf16_f32 v42, v32, v33
	v_cvt_pk_bf16_f32 v43, v34, v35
	global_store_dwordx4 v[50:51], v[40:43], off offset:64
	s_and_saveexec_b64 s[20:21], vcc
	s_cbranch_execz .LBB0_305
	global_store_dwordx4 v[48:49], v[36:39], off offset:128 nt
	global_store_dwordx4 v[48:49], v[32:35], off offset:144 nt

.LBB0_327:
	v_cmp_ne_u64_e32 vcc, 0, v[32:33]
	v_cvt_pk_bf16_f32 v38, v28, v29
	v_cvt_pk_bf16_f32 v39, v30, v31
	v_cvt_pk_bf16_f32 v40, v24, v25
	v_cvt_pk_bf16_f32 v41, v26, v27
	v_lshl_add_u64 v[34:35], v[138:139], 1, v[36:37]
	v_lshl_add_u64 v[32:33], v[138:139], 2, v[32:33]
	global_store_dwordx4 v[34:35], v[38:41], off
	s_and_saveexec_b64 s[20:21], vcc
	s_cbranch_execz .LBB0_329
	global_store_dwordx4 v[32:33], v[28:31], off nt
	global_store_dwordx4 v[32:33], v[24:27], off offset:16 nt
.LBB0_329:
	s_or_b64 exec, exec, s[20:21]
	s_nop 0
	v_cvt_pk_bf16_f32 v24, v20, v21
	v_cvt_pk_bf16_f32 v25, v22, v23
	v_cvt_pk_bf16_f32 v26, v16, v17
	v_cvt_pk_bf16_f32 v27, v18, v19
	global_store_dwordx4 v[34:35], v[24:27], off offset:64
	s_and_saveexec_b64 s[20:21], vcc
	s_cbranch_execz .LBB0_331
	global_store_dwordx4 v[32:33], v[20:23], off offset:128 nt
	global_store_dwordx4 v[32:33], v[16:19], off offset:144 nt

.LBB0_353:
	v_cmp_ne_u64_e32 vcc, 0, v[16:17]
	v_cvt_pk_bf16_f32 v22, v12, v13
	v_cvt_pk_bf16_f32 v23, v14, v15
	v_cvt_pk_bf16_f32 v24, v8, v9
	v_cvt_pk_bf16_f32 v25, v10, v11
	v_lshl_add_u64 v[18:19], v[138:139], 1, v[20:21]
	v_lshl_add_u64 v[16:17], v[138:139], 2, v[16:17]
	global_store_dwordx4 v[18:19], v[22:25], off
	s_and_saveexec_b64 s[4:5], vcc
	s_cbranch_execz .LBB0_355
	global_store_dwordx4 v[16:17], v[12:15], off nt
	global_store_dwordx4 v[16:17], v[8:11], off offset:16 nt
.LBB0_355:
	s_or_b64 exec, exec, s[4:5]
	s_nop 0
	v_cvt_pk_bf16_f32 v8, v4, v5
	v_cvt_pk_bf16_f32 v9, v6, v7
	v_cvt_pk_bf16_f32 v10, v0, v1
	v_cvt_pk_bf16_f32 v11, v2, v3
	global_store_dwordx4 v[18:19], v[8:11], off offset:64
	s_and_saveexec_b64 s[4:5], vcc
	s_cbranch_execz .LBB0_357
	global_store_dwordx4 v[16:17], v[4:7], off offset:128 nt
	global_store_dwordx4 v[16:17], v[0:3], off offset:144 nt

.LBB0_1017:
	v_lshl_add_u32 v148, s26, 8, v152
	v_mov_b32_e32 v149, 0
	v_lshl_add_u32 v146, s48, 8, v154
	v_mov_b32_e32 v147, 0
	v_lshlrev_b64 v[150:151], 11, v[148:149]
	v_lshlrev_b64 v[144:145], 1, v[146:147]
	v_lshl_add_u64 v[250:251], s[2:3], 0, v[150:151]
	v_lshl_add_u64 v[250:251], v[250:251], 0, v[144:145]
	v_lshl_add_u64 v[252:253], s[8:9], 0, v[150:151]
	v_lshl_add_u64 v[252:253], v[252:253], 0, v[144:145]
	v_lshlrev_b64 v[150:151], 12, v[148:149]
	v_lshlrev_b64 v[144:145], 2, v[146:147]
	v_lshl_add_u64 v[224:225], s[12:13], 0, v[150:151]
	v_lshl_add_u64 v[224:225], v[224:225], 0, v[144:145]
	s_mov_b64 s[28:29], 0x8000
	s_mov_b64 s[30:31], 0x28000
	s_mov_b64 s[50:51], 0x10000
	s_mov_b64 s[52:53], 0x50000
	s_and_b64 vcc, s[0:1], exec
	s_cselect_b32 s17, s18, s26
	global_load_dwordx4 v[160:163], v[250:251], off
	global_load_dwordx4 v[164:167], v[252:253], off nt
	global_load_dwordx4 v[168:171], v[250:251], off offset:256
	global_load_dwordx4 v[172:175], v[252:253], off offset:256 nt
	v_lshl_add_u64 v[250:251], v[250:251], 0, s[28:29]
	v_lshl_add_u64 v[252:253], v[252:253], 0, s[28:29]
	global_load_dwordx4 v[176:179], v[250:251], off
	global_load_dwordx4 v[180:183], v[252:253], off nt
	global_load_dwordx4 v[184:187], v[250:251], off offset:256
	global_load_dwordx4 v[188:191], v[252:253], off offset:256 nt
	v_lshl_add_u64 v[250:251], v[250:251], 0, s[28:29]
	v_lshl_add_u64 v[252:253], v[252:253], 0, s[28:29]
	global_load_dwordx4 v[192:195], v[250:251], off
	global_load_dwordx4 v[196:199], v[252:253], off nt
	global_load_dwordx4 v[200:203], v[250:251], off offset:256
	global_load_dwordx4 v[204:207], v[252:253], off offset:256 nt
	v_lshl_add_u64 v[250:251], v[250:251], 0, s[28:29]
	v_lshl_add_u64 v[252:253], v[252:253], 0, s[28:29]
	global_load_dwordx4 v[208:211], v[250:251], off
	global_load_dwordx4 v[212:215], v[252:253], off nt
	global_load_dwordx4 v[216:219], v[250:251], off offset:256
	global_load_dwordx4 v[220:223], v[252:253], off offset:256 nt
	v_lshl_add_u64 v[250:251], v[250:251], 0, s[30:31]
	v_lshl_add_u64 v[252:253], v[252:253], 0, s[30:31]
	s_waitcnt vmcnt(12)
	v_pk_mul_f32 v[124:125], v[124:125], v[226:227] op_sel_hi:[1,0]
	v_pk_mul_f32 v[126:127], v[126:127], v[226:227] op_sel_hi:[1,0]
	v_pk_mul_f32 v[120:121], v[120:121], v[226:227] op_sel_hi:[1,0]
	v_pk_mul_f32 v[122:123], v[122:123], v[226:227] op_sel_hi:[1,0]
	v_mul_f32_e32 v124, 0xbfb8aa3b, v124
	v_mul_f32_e32 v125, 0xbfb8aa3b, v125
	v_mul_f32_e32 v126, 0xbfb8aa3b, v126
	v_mul_f32_e32 v127, 0xbfb8aa3b, v127
	v_mul_f32_e32 v120, 0xbfb8aa3b, v120
	v_mul_f32_e32 v121, 0xbfb8aa3b, v121
	v_mul_f32_e32 v122, 0xbfb8aa3b, v122
	v_mul_f32_e32 v123, 0xbfb8aa3b, v123
	v_exp_f32_e32 v124, v124
	v_exp_f32_e32 v125, v125
	v_exp_f32_e32 v126, v126
	v_exp_f32_e32 v127, v127
	v_exp_f32_e32 v120, v120
	v_exp_f32_e32 v121, v121
	v_exp_f32_e32 v122, v122
	v_exp_f32_e32 v123, v123
	v_add_f32_e32 v124, 1.0, v124
	v_add_f32_e32 v125, 1.0, v125
	v_add_f32_e32 v126, 1.0, v126
	v_add_f32_e32 v127, 1.0, v127
	v_add_f32_e32 v120, 1.0, v120
	v_add_f32_e32 v121, 1.0, v121
	v_add_f32_e32 v122, 1.0, v122
	v_add_f32_e32 v123, 1.0, v123
	v_rcp_f32_e32 v124, v124
	v_rcp_f32_e32 v125, v125
	v_rcp_f32_e32 v126, v126
	v_rcp_f32_e32 v127, v127
	v_rcp_f32_e32 v120, v120
	v_rcp_f32_e32 v121, v121
	v_rcp_f32_e32 v122, v122
	v_rcp_f32_e32 v123, v123
	v_lshlrev_b32_e32 v144, 16, v160
	v_and_b32_e32 v145, 0xffff0000, v160
	v_lshlrev_b32_e32 v242, 16, v164
	v_and_b32_e32 v243, 0xffff0000, v164
	v_lshlrev_b32_e32 v146, 16, v161
	v_and_b32_e32 v147, 0xffff0000, v161
	v_lshlrev_b32_e32 v244, 16, v165
	v_and_b32_e32 v245, 0xffff0000, v165
	v_lshlrev_b32_e32 v148, 16, v162
	v_and_b32_e32 v149, 0xffff0000, v162
	v_lshlrev_b32_e32 v246, 16, v166
	v_and_b32_e32 v247, 0xffff0000, v166
	v_lshlrev_b32_e32 v150, 16, v163
	v_and_b32_e32 v151, 0xffff0000, v163
	v_lshlrev_b32_e32 v248, 16, v167
	v_and_b32_e32 v249, 0xffff0000, v167
	v_pk_fma_f32 v[124:125], v[124:125], v[242:243], v[144:145]
	v_pk_fma_f32 v[126:127], v[126:127], v[244:245], v[146:147]
	v_pk_fma_f32 v[120:121], v[120:121], v[246:247], v[148:149]
	v_pk_fma_f32 v[122:123], v[122:123], v[248:249], v[150:151]
	global_store_dwordx4 v[224:225], v[124:127], off nt
	global_store_dwordx4 v[224:225], v[120:123], off offset:16 nt
	v_pk_mul_f32 v[116:117], v[116:117], v[226:227] op_sel_hi:[1,0]
	v_pk_mul_f32 v[118:119], v[118:119], v[226:227] op_sel_hi:[1,0]
	v_pk_mul_f32 v[112:113], v[112:113], v[226:227] op_sel_hi:[1,0]
	v_pk_mul_f32 v[114:115], v[114:115], v[226:227] op_sel_hi:[1,0]
	v_mul_f32_e32 v116, 0xbfb8aa3b, v116
	v_mul_f32_e32 v117, 0xbfb8aa3b, v117
	v_mul_f32_e32 v118, 0xbfb8aa3b, v118
	v_mul_f32_e32 v119, 0xbfb8aa3b, v119
	v_mul_f32_e32 v112, 0xbfb8aa3b, v112
	v_mul_f32_e32 v113, 0xbfb8aa3b, v113
	v_mul_f32_e32 v114, 0xbfb8aa3b, v114
	v_mul_f32_e32 v115, 0xbfb8aa3b, v115
	v_exp_f32_e32 v116, v116
	v_exp_f32_e32 v117, v117
	v_exp_f32_e32 v118, v118
	v_exp_f32_e32 v119, v119
	v_exp_f32_e32 v112, v112
	v_exp_f32_e32 v113, v113
	v_exp_f32_e32 v114, v114
	v_exp_f32_e32 v115, v115
	v_add_f32_e32 v116, 1.0, v116
	v_add_f32_e32 v117, 1.0, v117
	v_add_f32_e32 v118, 1.0, v118
	v_add_f32_e32 v119, 1.0, v119
	v_add_f32_e32 v112, 1.0, v112
	v_add_f32_e32 v113, 1.0, v113
	v_add_f32_e32 v114, 1.0, v114
	v_add_f32_e32 v115, 1.0, v115
	v_rcp_f32_e32 v116, v116
	v_rcp_f32_e32 v117, v117
	v_rcp_f32_e32 v118, v118
	v_rcp_f32_e32 v119, v119
	v_rcp_f32_e32 v112, v112
	v_rcp_f32_e32 v113, v113
	v_rcp_f32_e32 v114, v114
	v_rcp_f32_e32 v115, v115
	v_lshlrev_b32_e32 v144, 16, v168
	v_and_b32_e32 v145, 0xffff0000, v168
	v_lshlrev_b32_e32 v242, 16, v172
	v_and_b32_e32 v243, 0xffff0000, v172
	v_lshlrev_b32_e32 v146, 16, v169
	v_and_b32_e32 v147, 0xffff0000, v169
	v_lshlrev_b32_e32 v244, 16, v173
	v_and_b32_e32 v245, 0xffff0000, v173
	v_lshlrev_b32_e32 v148, 16, v170
	v_and_b32_e32 v149, 0xffff0000, v170
	v_lshlrev_b32_e32 v246, 16, v174
	v_and_b32_e32 v247, 0xffff0000, v174
	v_lshlrev_b32_e32 v150, 16, v171
	v_and_b32_e32 v151, 0xffff0000, v171
	v_lshlrev_b32_e32 v248, 16, v175
	v_and_b32_e32 v249, 0xffff0000, v175
	v_pk_fma_f32 v[116:117], v[116:117], v[242:243], v[144:145]
	v_pk_fma_f32 v[118:119], v[118:119], v[244:245], v[146:147]
	v_pk_fma_f32 v[112:113], v[112:113], v[246:247], v[148:149]
	v_pk_fma_f32 v[114:115], v[114:115], v[248:249], v[150:151]
	global_store_dwordx4 v[224:225], v[116:119], off offset:512 nt
	global_store_dwordx4 v[224:225], v[112:115], off offset:528 nt
	v_lshl_add_u64 v[224:225], v[224:225], 0, s[50:51]
	global_load_dwordx4 v[160:163], v[250:251], off
	global_load_dwordx4 v[164:167], v[252:253], off nt
	global_load_dwordx4 v[168:171], v[250:251], off offset:256
	global_load_dwordx4 v[172:175], v[252:253], off offset:256 nt
	v_lshl_add_u64 v[250:251], v[250:251], 0, s[28:29]
	v_lshl_add_u64 v[252:253], v[252:253], 0, s[28:29]
	s_waitcnt vmcnt(16)
	v_pk_mul_f32 v[108:109], v[108:109], v[228:229] op_sel_hi:[1,0]
	v_pk_mul_f32 v[110:111], v[110:111], v[228:229] op_sel_hi:[1,0]
	v_pk_mul_f32 v[104:105], v[104:105], v[228:229] op_sel_hi:[1,0]
	v_pk_mul_f32 v[106:107], v[106:107], v[228:229] op_sel_hi:[1,0]
	v_mul_f32_e32 v108, 0xbfb8aa3b, v108
	v_mul_f32_e32 v109, 0xbfb8aa3b, v109
	v_mul_f32_e32 v110, 0xbfb8aa3b, v110
	v_mul_f32_e32 v111, 0xbfb8aa3b, v111
	v_mul_f32_e32 v104, 0xbfb8aa3b, v104
	v_mul_f32_e32 v105, 0xbfb8aa3b, v105
	v_mul_f32_e32 v106, 0xbfb8aa3b, v106
	v_mul_f32_e32 v107, 0xbfb8aa3b, v107
	v_exp_f32_e32 v108, v108
	v_exp_f32_e32 v109, v109
	v_exp_f32_e32 v110, v110
	v_exp_f32_e32 v111, v111
	v_exp_f32_e32 v104, v104
	v_exp_f32_e32 v105, v105
	v_exp_f32_e32 v106, v106
	v_exp_f32_e32 v107, v107
	v_add_f32_e32 v108, 1.0, v108
	v_add_f32_e32 v109, 1.0, v109
	v_add_f32_e32 v110, 1.0, v110
	v_add_f32_e32 v111, 1.0, v111
	v_add_f32_e32 v104, 1.0, v104
	v_add_f32_e32 v105, 1.0, v105
	v_add_f32_e32 v106, 1.0, v106
	v_add_f32_e32 v107, 1.0, v107
	v_rcp_f32_e32 v108, v108
	v_rcp_f32_e32 v109, v109
	v_rcp_f32_e32 v110, v110
	v_rcp_f32_e32 v111, v111
	v_rcp_f32_e32 v104, v104
	v_rcp_f32_e32 v105, v105
	v_rcp_f32_e32 v106, v106
	v_rcp_f32_e32 v107, v107
	v_lshlrev_b32_e32 v144, 16, v176
	v_and_b32_e32 v145, 0xffff0000, v176
	v_lshlrev_b32_e32 v242, 16, v180
	v_and_b32_e32 v243, 0xffff0000, v180
	v_lshlrev_b32_e32 v146, 16, v177
	v_and_b32_e32 v147, 0xffff0000, v177
	v_lshlrev_b32_e32 v244, 16, v181
	v_and_b32_e32 v245, 0xffff0000, v181
	v_lshlrev_b32_e32 v148, 16, v178
	v_and_b32_e32 v149, 0xffff0000, v178
	v_lshlrev_b32_e32 v246, 16, v182
	v_and_b32_e32 v247, 0xffff0000, v182
	v_lshlrev_b32_e32 v150, 16, v179
	v_and_b32_e32 v151, 0xffff0000, v179
	v_lshlrev_b32_e32 v248, 16, v183
	v_and_b32_e32 v249, 0xffff0000, v183
	v_pk_fma_f32 v[108:109], v[108:109], v[242:243], v[144:145]
	v_pk_fma_f32 v[110:111], v[110:111], v[244:245], v[146:147]
	v_pk_fma_f32 v[104:105], v[104:105], v[246:247], v[148:149]
	v_pk_fma_f32 v[106:107], v[106:107], v[248:249], v[150:151]
	global_store_dwordx4 v[224:225], v[108:111], off nt
	global_store_dwordx4 v[224:225], v[104:107], off offset:16 nt
	v_pk_mul_f32 v[100:101], v[100:101], v[228:229] op_sel_hi:[1,0]
	v_pk_mul_f32 v[102:103], v[102:103], v[228:229] op_sel_hi:[1,0]
	v_pk_mul_f32 v[96:97], v[96:97], v[228:229] op_sel_hi:[1,0]
	v_pk_mul_f32 v[98:99], v[98:99], v[228:229] op_sel_hi:[1,0]
	v_mul_f32_e32 v100, 0xbfb8aa3b, v100
	v_mul_f32_e32 v101, 0xbfb8aa3b, v101
	v_mul_f32_e32 v102, 0xbfb8aa3b, v102
	v_mul_f32_e32 v103, 0xbfb8aa3b, v103
	v_mul_f32_e32 v96, 0xbfb8aa3b, v96
	v_mul_f32_e32 v97, 0xbfb8aa3b, v97
	v_mul_f32_e32 v98, 0xbfb8aa3b, v98
	v_mul_f32_e32 v99, 0xbfb8aa3b, v99
	v_exp_f32_e32 v100, v100
	v_exp_f32_e32 v101, v101
	v_exp_f32_e32 v102, v102
	v_exp_f32_e32 v103, v103
	v_exp_f32_e32 v96, v96
	v_exp_f32_e32 v97, v97
	v_exp_f32_e32 v98, v98
	v_exp_f32_e32 v99, v99
	v_add_f32_e32 v100, 1.0, v100
	v_add_f32_e32 v101, 1.0, v101
	v_add_f32_e32 v102, 1.0, v102
	v_add_f32_e32 v103, 1.0, v103
	v_add_f32_e32 v96, 1.0, v96
	v_add_f32_e32 v97, 1.0, v97
	v_add_f32_e32 v98, 1.0, v98
	v_add_f32_e32 v99, 1.0, v99
	v_rcp_f32_e32 v100, v100
	v_rcp_f32_e32 v101, v101
	v_rcp_f32_e32 v102, v102
	v_rcp_f32_e32 v103, v103
	v_rcp_f32_e32 v96, v96
	v_rcp_f32_e32 v97, v97
	v_rcp_f32_e32 v98, v98
	v_rcp_f32_e32 v99, v99
	v_lshlrev_b32_e32 v144, 16, v184
	v_and_b32_e32 v145, 0xffff0000, v184
	v_lshlrev_b32_e32 v242, 16, v188
	v_and_b32_e32 v243, 0xffff0000, v188
	v_lshlrev_b32_e32 v146, 16, v185
	v_and_b32_e32 v147, 0xffff0000, v185
	v_lshlrev_b32_e32 v244, 16, v189
	v_and_b32_e32 v245, 0xffff0000, v189
	v_lshlrev_b32_e32 v148, 16, v186
	v_and_b32_e32 v149, 0xffff0000, v186
	v_lshlrev_b32_e32 v246, 16, v190
	v_and_b32_e32 v247, 0xffff0000, v190
	v_lshlrev_b32_e32 v150, 16, v187
	v_and_b32_e32 v151, 0xffff0000, v187
	v_lshlrev_b32_e32 v248, 16, v191
	v_and_b32_e32 v249, 0xffff0000, v191
	v_pk_fma_f32 v[100:101], v[100:101], v[242:243], v[144:145]
	v_pk_fma_f32 v[102:103], v[102:103], v[244:245], v[146:147]
	v_pk_fma_f32 v[96:97], v[96:97], v[246:247], v[148:149]
	v_pk_fma_f32 v[98:99], v[98:99], v[248:249], v[150:151]
	global_store_dwordx4 v[224:225], v[100:103], off offset:512 nt
	global_store_dwordx4 v[224:225], v[96:99], off offset:528 nt
	v_lshl_add_u64 v[224:225], v[224:225], 0, s[50:51]
	global_load_dwordx4 v[176:179], v[250:251], off
	global_load_dwordx4 v[180:183], v[252:253], off nt
	global_load_dwordx4 v[184:187], v[250:251], off offset:256
	global_load_dwordx4 v[188:191], v[252:253], off offset:256 nt
	v_lshl_add_u64 v[250:251], v[250:251], 0, s[28:29]
	v_lshl_add_u64 v[252:253], v[252:253], 0, s[28:29]
	v_lshl_add_u32 v144, s17, 8, v152
	v_mov_b32_e32 v145, 0
	v_lshlrev_b64 v[144:145], 6, v[144:145]
	v_and_b32_e32 v146, 24, v154
	v_lshlrev_b32_e32 v146, 1, v146
	v_mov_b32_e32 v147, 0
	v_lshl_add_u64 v[144:145], s[6:7], 0, v[144:145]
	v_lshl_add_u64 v[144:145], v[144:145], 0, v[146:147]
	global_load_dwordx4 v[112:115], v[144:145], off
	global_load_dwordx4 v[116:119], v[144:145], off offset:1024
	global_load_dwordx4 v[120:123], v[144:145], off offset:2048
	global_load_dwordx4 v[124:127], v[144:145], off offset:3072
	v_add_co_u32_e32 v144, vcc, 0x2000, v144
	s_nop 1
	v_addc_co_u32_e32 v145, vcc, 0, v145, vcc
	global_load_dwordx4 v[96:99], v[144:145], off
	global_load_dwordx4 v[100:103], v[144:145], off offset:1024
	global_load_dwordx4 v[104:107], v[144:145], off offset:2048
	global_load_dwordx4 v[108:111], v[144:145], off offset:3072
	s_waitcnt vmcnt(28)
	v_pk_mul_f32 v[92:93], v[92:93], v[230:231] op_sel_hi:[1,0]
	v_pk_mul_f32 v[94:95], v[94:95], v[230:231] op_sel_hi:[1,0]
	v_pk_mul_f32 v[88:89], v[88:89], v[230:231] op_sel_hi:[1,0]
	v_pk_mul_f32 v[90:91], v[90:91], v[230:231] op_sel_hi:[1,0]
	v_mul_f32_e32 v92, 0xbfb8aa3b, v92
	v_mul_f32_e32 v93, 0xbfb8aa3b, v93
	v_mul_f32_e32 v94, 0xbfb8aa3b, v94
	v_mul_f32_e32 v95, 0xbfb8aa3b, v95
	v_mul_f32_e32 v88, 0xbfb8aa3b, v88
	v_mul_f32_e32 v89, 0xbfb8aa3b, v89
	v_mul_f32_e32 v90, 0xbfb8aa3b, v90
	v_mul_f32_e32 v91, 0xbfb8aa3b, v91
	v_exp_f32_e32 v92, v92
	v_exp_f32_e32 v93, v93
	v_exp_f32_e32 v94, v94
	v_exp_f32_e32 v95, v95
	v_exp_f32_e32 v88, v88
	v_exp_f32_e32 v89, v89
	v_exp_f32_e32 v90, v90
	v_exp_f32_e32 v91, v91
	v_add_f32_e32 v92, 1.0, v92
	v_add_f32_e32 v93, 1.0, v93
	v_add_f32_e32 v94, 1.0, v94
	v_add_f32_e32 v95, 1.0, v95
	v_add_f32_e32 v88, 1.0, v88
	v_add_f32_e32 v89, 1.0, v89
	v_add_f32_e32 v90, 1.0, v90
	v_add_f32_e32 v91, 1.0, v91
	v_rcp_f32_e32 v92, v92
	v_rcp_f32_e32 v93, v93
	v_rcp_f32_e32 v94, v94
	v_rcp_f32_e32 v95, v95
	v_rcp_f32_e32 v88, v88
	v_rcp_f32_e32 v89, v89
	v_rcp_f32_e32 v90, v90
	v_rcp_f32_e32 v91, v91
	v_lshlrev_b32_e32 v144, 16, v192
	v_and_b32_e32 v145, 0xffff0000, v192
	v_lshlrev_b32_e32 v242, 16, v196
	v_and_b32_e32 v243, 0xffff0000, v196
	v_lshlrev_b32_e32 v146, 16, v193
	v_and_b32_e32 v147, 0xffff0000, v193
	v_lshlrev_b32_e32 v244, 16, v197
	v_and_b32_e32 v245, 0xffff0000, v197
	v_lshlrev_b32_e32 v148, 16, v194
	v_and_b32_e32 v149, 0xffff0000, v194
	v_lshlrev_b32_e32 v246, 16, v198
	v_and_b32_e32 v247, 0xffff0000, v198
	v_lshlrev_b32_e32 v150, 16, v195
	v_and_b32_e32 v151, 0xffff0000, v195
	v_lshlrev_b32_e32 v248, 16, v199
	v_and_b32_e32 v249, 0xffff0000, v199
	v_pk_fma_f32 v[92:93], v[92:93], v[242:243], v[144:145]
	v_pk_fma_f32 v[94:95], v[94:95], v[244:245], v[146:147]
	v_pk_fma_f32 v[88:89], v[88:89], v[246:247], v[148:149]
	v_pk_fma_f32 v[90:91], v[90:91], v[248:249], v[150:151]
	global_store_dwordx4 v[224:225], v[92:95], off nt
	global_store_dwordx4 v[224:225], v[88:91], off offset:16 nt
	v_pk_mul_f32 v[84:85], v[84:85], v[230:231] op_sel_hi:[1,0]
	v_pk_mul_f32 v[86:87], v[86:87], v[230:231] op_sel_hi:[1,0]
	v_pk_mul_f32 v[80:81], v[80:81], v[230:231] op_sel_hi:[1,0]
	v_pk_mul_f32 v[82:83], v[82:83], v[230:231] op_sel_hi:[1,0]
	v_mul_f32_e32 v84, 0xbfb8aa3b, v84
	v_mul_f32_e32 v85, 0xbfb8aa3b, v85
	v_mul_f32_e32 v86, 0xbfb8aa3b, v86
	v_mul_f32_e32 v87, 0xbfb8aa3b, v87
	v_mul_f32_e32 v80, 0xbfb8aa3b, v80
	v_mul_f32_e32 v81, 0xbfb8aa3b, v81
	v_mul_f32_e32 v82, 0xbfb8aa3b, v82
	v_mul_f32_e32 v83, 0xbfb8aa3b, v83
	v_exp_f32_e32 v84, v84
	v_exp_f32_e32 v85, v85
	v_exp_f32_e32 v86, v86
	v_exp_f32_e32 v87, v87
	v_exp_f32_e32 v80, v80
	v_exp_f32_e32 v81, v81
	v_exp_f32_e32 v82, v82
	v_exp_f32_e32 v83, v83
	v_add_f32_e32 v84, 1.0, v84
	v_add_f32_e32 v85, 1.0, v85
	v_add_f32_e32 v86, 1.0, v86
	v_add_f32_e32 v87, 1.0, v87
	v_add_f32_e32 v80, 1.0, v80
	v_add_f32_e32 v81, 1.0, v81
	v_add_f32_e32 v82, 1.0, v82
	v_add_f32_e32 v83, 1.0, v83
	v_rcp_f32_e32 v84, v84
	v_rcp_f32_e32 v85, v85
	v_rcp_f32_e32 v86, v86
	v_rcp_f32_e32 v87, v87
	v_rcp_f32_e32 v80, v80
	v_rcp_f32_e32 v81, v81
	v_rcp_f32_e32 v82, v82
	v_rcp_f32_e32 v83, v83
	v_lshlrev_b32_e32 v144, 16, v200
	v_and_b32_e32 v145, 0xffff0000, v200
	v_lshlrev_b32_e32 v242, 16, v204
	v_and_b32_e32 v243, 0xffff0000, v204
	v_lshlrev_b32_e32 v146, 16, v201
	v_and_b32_e32 v147, 0xffff0000, v201
	v_lshlrev_b32_e32 v244, 16, v205
	v_and_b32_e32 v245, 0xffff0000, v205
	v_lshlrev_b32_e32 v148, 16, v202
	v_and_b32_e32 v149, 0xffff0000, v202
	v_lshlrev_b32_e32 v246, 16, v206
	v_and_b32_e32 v247, 0xffff0000, v206
	v_lshlrev_b32_e32 v150, 16, v203
	v_and_b32_e32 v151, 0xffff0000, v203
	v_lshlrev_b32_e32 v248, 16, v207
	v_and_b32_e32 v249, 0xffff0000, v207
	v_pk_fma_f32 v[84:85], v[84:85], v[242:243], v[144:145]
	v_pk_fma_f32 v[86:87], v[86:87], v[244:245], v[146:147]
	v_pk_fma_f32 v[80:81], v[80:81], v[246:247], v[148:149]
	v_pk_fma_f32 v[82:83], v[82:83], v[248:249], v[150:151]
	global_store_dwordx4 v[224:225], v[84:87], off offset:512 nt
	global_store_dwordx4 v[224:225], v[80:83], off offset:528 nt
	v_lshl_add_u64 v[224:225], v[224:225], 0, s[50:51]
	global_load_dwordx4 v[192:195], v[250:251], off
	global_load_dwordx4 v[196:199], v[252:253], off nt
	global_load_dwordx4 v[200:203], v[250:251], off offset:256
	global_load_dwordx4 v[204:207], v[252:253], off offset:256 nt
	v_lshl_add_u64 v[250:251], v[250:251], 0, s[28:29]
	v_lshl_add_u64 v[252:253], v[252:253], 0, s[28:29]
	s_waitcnt vmcnt(32)
	v_pk_mul_f32 v[76:77], v[76:77], v[232:233] op_sel_hi:[1,0]
	v_pk_mul_f32 v[78:79], v[78:79], v[232:233] op_sel_hi:[1,0]
	v_pk_mul_f32 v[72:73], v[72:73], v[232:233] op_sel_hi:[1,0]
	v_pk_mul_f32 v[74:75], v[74:75], v[232:233] op_sel_hi:[1,0]
	v_mul_f32_e32 v76, 0xbfb8aa3b, v76
	v_mul_f32_e32 v77, 0xbfb8aa3b, v77
	v_mul_f32_e32 v78, 0xbfb8aa3b, v78
	v_mul_f32_e32 v79, 0xbfb8aa3b, v79
	v_mul_f32_e32 v72, 0xbfb8aa3b, v72
	v_mul_f32_e32 v73, 0xbfb8aa3b, v73
	v_mul_f32_e32 v74, 0xbfb8aa3b, v74
	v_mul_f32_e32 v75, 0xbfb8aa3b, v75
	v_exp_f32_e32 v76, v76
	v_exp_f32_e32 v77, v77
	v_exp_f32_e32 v78, v78
	v_exp_f32_e32 v79, v79
	v_exp_f32_e32 v72, v72
	v_exp_f32_e32 v73, v73
	v_exp_f32_e32 v74, v74
	v_exp_f32_e32 v75, v75
	v_add_f32_e32 v76, 1.0, v76
	v_add_f32_e32 v77, 1.0, v77
	v_add_f32_e32 v78, 1.0, v78
	v_add_f32_e32 v79, 1.0, v79
	v_add_f32_e32 v72, 1.0, v72
	v_add_f32_e32 v73, 1.0, v73
	v_add_f32_e32 v74, 1.0, v74
	v_add_f32_e32 v75, 1.0, v75
	v_rcp_f32_e32 v76, v76
	v_rcp_f32_e32 v77, v77
	v_rcp_f32_e32 v78, v78
	v_rcp_f32_e32 v79, v79
	v_rcp_f32_e32 v72, v72
	v_rcp_f32_e32 v73, v73
	v_rcp_f32_e32 v74, v74
	v_rcp_f32_e32 v75, v75
	v_lshlrev_b32_e32 v144, 16, v208
	v_and_b32_e32 v145, 0xffff0000, v208
	v_lshlrev_b32_e32 v242, 16, v212
	v_and_b32_e32 v243, 0xffff0000, v212
	v_lshlrev_b32_e32 v146, 16, v209
	v_and_b32_e32 v147, 0xffff0000, v209
	v_lshlrev_b32_e32 v244, 16, v213
	v_and_b32_e32 v245, 0xffff0000, v213
	v_lshlrev_b32_e32 v148, 16, v210
	v_and_b32_e32 v149, 0xffff0000, v210
	v_lshlrev_b32_e32 v246, 16, v214
	v_and_b32_e32 v247, 0xffff0000, v214
	v_lshlrev_b32_e32 v150, 16, v211
	v_and_b32_e32 v151, 0xffff0000, v211
	v_lshlrev_b32_e32 v248, 16, v215
	v_and_b32_e32 v249, 0xffff0000, v215
	v_pk_fma_f32 v[76:77], v[76:77], v[242:243], v[144:145]
	v_pk_fma_f32 v[78:79], v[78:79], v[244:245], v[146:147]
	v_pk_fma_f32 v[72:73], v[72:73], v[246:247], v[148:149]
	v_pk_fma_f32 v[74:75], v[74:75], v[248:249], v[150:151]
	global_store_dwordx4 v[224:225], v[76:79], off nt
	global_store_dwordx4 v[224:225], v[72:75], off offset:16 nt
	v_pk_mul_f32 v[68:69], v[68:69], v[232:233] op_sel_hi:[1,0]
	v_pk_mul_f32 v[70:71], v[70:71], v[232:233] op_sel_hi:[1,0]
	v_pk_mul_f32 v[64:65], v[64:65], v[232:233] op_sel_hi:[1,0]
	v_pk_mul_f32 v[66:67], v[66:67], v[232:233] op_sel_hi:[1,0]
	v_mul_f32_e32 v68, 0xbfb8aa3b, v68
	v_mul_f32_e32 v69, 0xbfb8aa3b, v69
	v_mul_f32_e32 v70, 0xbfb8aa3b, v70
	v_mul_f32_e32 v71, 0xbfb8aa3b, v71
	v_mul_f32_e32 v64, 0xbfb8aa3b, v64
	v_mul_f32_e32 v65, 0xbfb8aa3b, v65
	v_mul_f32_e32 v66, 0xbfb8aa3b, v66
	v_mul_f32_e32 v67, 0xbfb8aa3b, v67
	v_exp_f32_e32 v68, v68
	v_exp_f32_e32 v69, v69
	v_exp_f32_e32 v70, v70
	v_exp_f32_e32 v71, v71
	v_exp_f32_e32 v64, v64
	v_exp_f32_e32 v65, v65
	v_exp_f32_e32 v66, v66
	v_exp_f32_e32 v67, v67
	v_add_f32_e32 v68, 1.0, v68
	v_add_f32_e32 v69, 1.0, v69
	v_add_f32_e32 v70, 1.0, v70
	v_add_f32_e32 v71, 1.0, v71
	v_add_f32_e32 v64, 1.0, v64
	v_add_f32_e32 v65, 1.0, v65
	v_add_f32_e32 v66, 1.0, v66
	v_add_f32_e32 v67, 1.0, v67
	v_rcp_f32_e32 v68, v68
	v_rcp_f32_e32 v69, v69
	v_rcp_f32_e32 v70, v70
	v_rcp_f32_e32 v71, v71
	v_rcp_f32_e32 v64, v64
	v_rcp_f32_e32 v65, v65
	v_rcp_f32_e32 v66, v66
	v_rcp_f32_e32 v67, v67
	v_lshlrev_b32_e32 v144, 16, v216
	v_and_b32_e32 v145, 0xffff0000, v216
	v_lshlrev_b32_e32 v242, 16, v220
	v_and_b32_e32 v243, 0xffff0000, v220
	v_lshlrev_b32_e32 v146, 16, v217
	v_and_b32_e32 v147, 0xffff0000, v217
	v_lshlrev_b32_e32 v244, 16, v221
	v_and_b32_e32 v245, 0xffff0000, v221
	v_lshlrev_b32_e32 v148, 16, v218
	v_and_b32_e32 v149, 0xffff0000, v218
	v_lshlrev_b32_e32 v246, 16, v222
	v_and_b32_e32 v247, 0xffff0000, v222
	v_lshlrev_b32_e32 v150, 16, v219
	v_and_b32_e32 v151, 0xffff0000, v219
	v_lshlrev_b32_e32 v248, 16, v223
	v_and_b32_e32 v249, 0xffff0000, v223
	v_pk_fma_f32 v[68:69], v[68:69], v[242:243], v[144:145]
	v_pk_fma_f32 v[70:71], v[70:71], v[244:245], v[146:147]
	v_pk_fma_f32 v[64:65], v[64:65], v[246:247], v[148:149]
	v_pk_fma_f32 v[66:67], v[66:67], v[248:249], v[150:151]
	global_store_dwordx4 v[224:225], v[68:71], off offset:512 nt
	global_store_dwordx4 v[224:225], v[64:67], off offset:528 nt
	v_lshl_add_u64 v[224:225], v[224:225], 0, s[52:53]
	global_load_dwordx4 v[208:211], v[250:251], off
	global_load_dwordx4 v[212:215], v[252:253], off nt
	global_load_dwordx4 v[216:219], v[250:251], off offset:256
	global_load_dwordx4 v[220:223], v[252:253], off offset:256 nt
	s_waitcnt vmcnt(32)
	v_pk_mul_f32 v[60:61], v[60:61], v[234:235] op_sel_hi:[1,0]
	v_pk_mul_f32 v[62:63], v[62:63], v[234:235] op_sel_hi:[1,0]
	v_pk_mul_f32 v[56:57], v[56:57], v[234:235] op_sel_hi:[1,0]
	v_pk_mul_f32 v[58:59], v[58:59], v[234:235] op_sel_hi:[1,0]
	v_mul_f32_e32 v60, 0xbfb8aa3b, v60
	v_mul_f32_e32 v61, 0xbfb8aa3b, v61
	v_mul_f32_e32 v62, 0xbfb8aa3b, v62
	v_mul_f32_e32 v63, 0xbfb8aa3b, v63
	v_mul_f32_e32 v56, 0xbfb8aa3b, v56
	v_mul_f32_e32 v57, 0xbfb8aa3b, v57
	v_mul_f32_e32 v58, 0xbfb8aa3b, v58
	v_mul_f32_e32 v59, 0xbfb8aa3b, v59
	v_exp_f32_e32 v60, v60
	v_exp_f32_e32 v61, v61
	v_exp_f32_e32 v62, v62
	v_exp_f32_e32 v63, v63
	v_exp_f32_e32 v56, v56
	v_exp_f32_e32 v57, v57
	v_exp_f32_e32 v58, v58
	v_exp_f32_e32 v59, v59
	v_add_f32_e32 v60, 1.0, v60
	v_add_f32_e32 v61, 1.0, v61
	v_add_f32_e32 v62, 1.0, v62
	v_add_f32_e32 v63, 1.0, v63
	v_add_f32_e32 v56, 1.0, v56
	v_add_f32_e32 v57, 1.0, v57
	v_add_f32_e32 v58, 1.0, v58
	v_add_f32_e32 v59, 1.0, v59
	v_rcp_f32_e32 v60, v60
	v_rcp_f32_e32 v61, v61
	v_rcp_f32_e32 v62, v62
	v_rcp_f32_e32 v63, v63
	v_rcp_f32_e32 v56, v56
	v_rcp_f32_e32 v57, v57
	v_rcp_f32_e32 v58, v58
	v_rcp_f32_e32 v59, v59
	v_lshlrev_b32_e32 v144, 16, v160
	v_and_b32_e32 v145, 0xffff0000, v160
	v_lshlrev_b32_e32 v242, 16, v164
	v_and_b32_e32 v243, 0xffff0000, v164
	v_lshlrev_b32_e32 v146, 16, v161
	v_and_b32_e32 v147, 0xffff0000, v161
	v_lshlrev_b32_e32 v244, 16, v165
	v_and_b32_e32 v245, 0xffff0000, v165
	v_lshlrev_b32_e32 v148, 16, v162
	v_and_b32_e32 v149, 0xffff0000, v162
	v_lshlrev_b32_e32 v246, 16, v166
	v_and_b32_e32 v247, 0xffff0000, v166
	v_lshlrev_b32_e32 v150, 16, v163
	v_and_b32_e32 v151, 0xffff0000, v163
	v_lshlrev_b32_e32 v248, 16, v167
	v_and_b32_e32 v249, 0xffff0000, v167
	v_pk_fma_f32 v[60:61], v[60:61], v[242:243], v[144:145]
	v_pk_fma_f32 v[62:63], v[62:63], v[244:245], v[146:147]
	v_pk_fma_f32 v[56:57], v[56:57], v[246:247], v[148:149]
	v_pk_fma_f32 v[58:59], v[58:59], v[248:249], v[150:151]
	global_store_dwordx4 v[224:225], v[60:63], off nt
	global_store_dwordx4 v[224:225], v[56:59], off offset:16 nt
	v_pk_mul_f32 v[52:53], v[52:53], v[234:235] op_sel_hi:[1,0]
	v_pk_mul_f32 v[54:55], v[54:55], v[234:235] op_sel_hi:[1,0]
	v_pk_mul_f32 v[48:49], v[48:49], v[234:235] op_sel_hi:[1,0]
	v_pk_mul_f32 v[50:51], v[50:51], v[234:235] op_sel_hi:[1,0]
	v_mul_f32_e32 v52, 0xbfb8aa3b, v52
	v_mul_f32_e32 v53, 0xbfb8aa3b, v53
	v_mul_f32_e32 v54, 0xbfb8aa3b, v54
	v_mul_f32_e32 v55, 0xbfb8aa3b, v55
	v_mul_f32_e32 v48, 0xbfb8aa3b, v48
	v_mul_f32_e32 v49, 0xbfb8aa3b, v49
	v_mul_f32_e32 v50, 0xbfb8aa3b, v50
	v_mul_f32_e32 v51, 0xbfb8aa3b, v51
	v_exp_f32_e32 v52, v52
	v_exp_f32_e32 v53, v53
	v_exp_f32_e32 v54, v54
	v_exp_f32_e32 v55, v55
	v_exp_f32_e32 v48, v48
	v_exp_f32_e32 v49, v49
	v_exp_f32_e32 v50, v50
	v_exp_f32_e32 v51, v51
	v_add_f32_e32 v52, 1.0, v52
	v_add_f32_e32 v53, 1.0, v53
	v_add_f32_e32 v54, 1.0, v54
	v_add_f32_e32 v55, 1.0, v55
	v_add_f32_e32 v48, 1.0, v48
	v_add_f32_e32 v49, 1.0, v49
	v_add_f32_e32 v50, 1.0, v50
	v_add_f32_e32 v51, 1.0, v51
	v_rcp_f32_e32 v52, v52
	v_rcp_f32_e32 v53, v53
	v_rcp_f32_e32 v54, v54
	v_rcp_f32_e32 v55, v55
	v_rcp_f32_e32 v48, v48
	v_rcp_f32_e32 v49, v49
	v_rcp_f32_e32 v50, v50
	v_rcp_f32_e32 v51, v51
	v_lshlrev_b32_e32 v144, 16, v168
	v_and_b32_e32 v145, 0xffff0000, v168
	v_lshlrev_b32_e32 v242, 16, v172
	v_and_b32_e32 v243, 0xffff0000, v172
	v_lshlrev_b32_e32 v146, 16, v169
	v_and_b32_e32 v147, 0xffff0000, v169
	v_lshlrev_b32_e32 v244, 16, v173
	v_and_b32_e32 v245, 0xffff0000, v173
	v_lshlrev_b32_e32 v148, 16, v170
	v_and_b32_e32 v149, 0xffff0000, v170
	v_lshlrev_b32_e32 v246, 16, v174
	v_and_b32_e32 v247, 0xffff0000, v174
	v_lshlrev_b32_e32 v150, 16, v171
	v_and_b32_e32 v151, 0xffff0000, v171
	v_lshlrev_b32_e32 v248, 16, v175
	v_and_b32_e32 v249, 0xffff0000, v175
	v_pk_fma_f32 v[52:53], v[52:53], v[242:243], v[144:145]
	v_pk_fma_f32 v[54:55], v[54:55], v[244:245], v[146:147]
	v_pk_fma_f32 v[48:49], v[48:49], v[246:247], v[148:149]
	v_pk_fma_f32 v[50:51], v[50:51], v[248:249], v[150:151]
	global_store_dwordx4 v[224:225], v[52:55], off offset:512 nt
	global_store_dwordx4 v[224:225], v[48:51], off offset:528 nt
	v_lshl_add_u64 v[224:225], v[224:225], 0, s[50:51]
	s_waitcnt vmcnt(28)
	v_pk_mul_f32 v[44:45], v[44:45], v[236:237] op_sel_hi:[1,0]
	v_pk_mul_f32 v[46:47], v[46:47], v[236:237] op_sel_hi:[1,0]
	v_pk_mul_f32 v[40:41], v[40:41], v[236:237] op_sel_hi:[1,0]
	v_pk_mul_f32 v[42:43], v[42:43], v[236:237] op_sel_hi:[1,0]
	v_mul_f32_e32 v44, 0xbfb8aa3b, v44
	v_mul_f32_e32 v45, 0xbfb8aa3b, v45
	v_mul_f32_e32 v46, 0xbfb8aa3b, v46
	v_mul_f32_e32 v47, 0xbfb8aa3b, v47
	v_mul_f32_e32 v40, 0xbfb8aa3b, v40
	v_mul_f32_e32 v41, 0xbfb8aa3b, v41
	v_mul_f32_e32 v42, 0xbfb8aa3b, v42
	v_mul_f32_e32 v43, 0xbfb8aa3b, v43
	v_exp_f32_e32 v44, v44
	v_exp_f32_e32 v45, v45
	v_exp_f32_e32 v46, v46
	v_exp_f32_e32 v47, v47
	v_exp_f32_e32 v40, v40
	v_exp_f32_e32 v41, v41
	v_exp_f32_e32 v42, v42
	v_exp_f32_e32 v43, v43
	v_add_f32_e32 v44, 1.0, v44
	v_add_f32_e32 v45, 1.0, v45
	v_add_f32_e32 v46, 1.0, v46
	v_add_f32_e32 v47, 1.0, v47
	v_add_f32_e32 v40, 1.0, v40
	v_add_f32_e32 v41, 1.0, v41
	v_add_f32_e32 v42, 1.0, v42
	v_add_f32_e32 v43, 1.0, v43
	v_rcp_f32_e32 v44, v44
	v_rcp_f32_e32 v45, v45
	v_rcp_f32_e32 v46, v46
	v_rcp_f32_e32 v47, v47
	v_rcp_f32_e32 v40, v40
	v_rcp_f32_e32 v41, v41
	v_rcp_f32_e32 v42, v42
	v_rcp_f32_e32 v43, v43
	v_lshlrev_b32_e32 v144, 16, v176
	v_and_b32_e32 v145, 0xffff0000, v176
	v_lshlrev_b32_e32 v242, 16, v180
	v_and_b32_e32 v243, 0xffff0000, v180
	v_lshlrev_b32_e32 v146, 16, v177
	v_and_b32_e32 v147, 0xffff0000, v177
	v_lshlrev_b32_e32 v244, 16, v181
	v_and_b32_e32 v245, 0xffff0000, v181
	v_lshlrev_b32_e32 v148, 16, v178
	v_and_b32_e32 v149, 0xffff0000, v178
	v_lshlrev_b32_e32 v246, 16, v182
	v_and_b32_e32 v247, 0xffff0000, v182
	v_lshlrev_b32_e32 v150, 16, v179
	v_and_b32_e32 v151, 0xffff0000, v179
	v_lshlrev_b32_e32 v248, 16, v183
	v_and_b32_e32 v249, 0xffff0000, v183
	v_pk_fma_f32 v[44:45], v[44:45], v[242:243], v[144:145]
	v_pk_fma_f32 v[46:47], v[46:47], v[244:245], v[146:147]
	v_pk_fma_f32 v[40:41], v[40:41], v[246:247], v[148:149]
	v_pk_fma_f32 v[42:43], v[42:43], v[248:249], v[150:151]
	global_store_dwordx4 v[224:225], v[44:47], off nt
	global_store_dwordx4 v[224:225], v[40:43], off offset:16 nt
	v_pk_mul_f32 v[36:37], v[36:37], v[236:237] op_sel_hi:[1,0]
	v_pk_mul_f32 v[38:39], v[38:39], v[236:237] op_sel_hi:[1,0]
	v_pk_mul_f32 v[32:33], v[32:33], v[236:237] op_sel_hi:[1,0]
	v_pk_mul_f32 v[34:35], v[34:35], v[236:237] op_sel_hi:[1,0]
	v_mul_f32_e32 v36, 0xbfb8aa3b, v36
	v_mul_f32_e32 v37, 0xbfb8aa3b, v37
	v_mul_f32_e32 v38, 0xbfb8aa3b, v38
	v_mul_f32_e32 v39, 0xbfb8aa3b, v39
	v_mul_f32_e32 v32, 0xbfb8aa3b, v32
	v_mul_f32_e32 v33, 0xbfb8aa3b, v33
	v_mul_f32_e32 v34, 0xbfb8aa3b, v34
	v_mul_f32_e32 v35, 0xbfb8aa3b, v35
	v_exp_f32_e32 v36, v36
	v_exp_f32_e32 v37, v37
	v_exp_f32_e32 v38, v38
	v_exp_f32_e32 v39, v39
	v_exp_f32_e32 v32, v32
	v_exp_f32_e32 v33, v33
	v_exp_f32_e32 v34, v34
	v_exp_f32_e32 v35, v35
	v_add_f32_e32 v36, 1.0, v36
	v_add_f32_e32 v37, 1.0, v37
	v_add_f32_e32 v38, 1.0, v38
	v_add_f32_e32 v39, 1.0, v39
	v_add_f32_e32 v32, 1.0, v32
	v_add_f32_e32 v33, 1.0, v33
	v_add_f32_e32 v34, 1.0, v34
	v_add_f32_e32 v35, 1.0, v35
	v_rcp_f32_e32 v36, v36
	v_rcp_f32_e32 v37, v37
	v_rcp_f32_e32 v38, v38
	v_rcp_f32_e32 v39, v39
	v_rcp_f32_e32 v32, v32
	v_rcp_f32_e32 v33, v33
	v_rcp_f32_e32 v34, v34
	v_rcp_f32_e32 v35, v35
	v_lshlrev_b32_e32 v144, 16, v184
	v_and_b32_e32 v145, 0xffff0000, v184
	v_lshlrev_b32_e32 v242, 16, v188
	v_and_b32_e32 v243, 0xffff0000, v188
	v_lshlrev_b32_e32 v146, 16, v185
	v_and_b32_e32 v147, 0xffff0000, v185
	v_lshlrev_b32_e32 v244, 16, v189
	v_and_b32_e32 v245, 0xffff0000, v189
	v_lshlrev_b32_e32 v148, 16, v186
	v_and_b32_e32 v149, 0xffff0000, v186
	v_lshlrev_b32_e32 v246, 16, v190
	v_and_b32_e32 v247, 0xffff0000, v190
	v_lshlrev_b32_e32 v150, 16, v187
	v_and_b32_e32 v151, 0xffff0000, v187
	v_lshlrev_b32_e32 v248, 16, v191
	v_and_b32_e32 v249, 0xffff0000, v191
	v_pk_fma_f32 v[36:37], v[36:37], v[242:243], v[144:145]
	v_pk_fma_f32 v[38:39], v[38:39], v[244:245], v[146:147]
	v_pk_fma_f32 v[32:33], v[32:33], v[246:247], v[148:149]
	v_pk_fma_f32 v[34:35], v[34:35], v[248:249], v[150:151]
	global_store_dwordx4 v[224:225], v[36:39], off offset:512 nt
	global_store_dwordx4 v[224:225], v[32:35], off offset:528 nt
	v_lshl_add_u64 v[224:225], v[224:225], 0, s[50:51]
	s_waitcnt vmcnt(16)
	v_pk_mul_f32 v[28:29], v[28:29], v[238:239] op_sel_hi:[1,0]
	v_pk_mul_f32 v[30:31], v[30:31], v[238:239] op_sel_hi:[1,0]
	v_pk_mul_f32 v[24:25], v[24:25], v[238:239] op_sel_hi:[1,0]
	v_pk_mul_f32 v[26:27], v[26:27], v[238:239] op_sel_hi:[1,0]
	v_mul_f32_e32 v28, 0xbfb8aa3b, v28
	v_mul_f32_e32 v29, 0xbfb8aa3b, v29
	v_mul_f32_e32 v30, 0xbfb8aa3b, v30
	v_mul_f32_e32 v31, 0xbfb8aa3b, v31
	v_mul_f32_e32 v24, 0xbfb8aa3b, v24
	v_mul_f32_e32 v25, 0xbfb8aa3b, v25
	v_mul_f32_e32 v26, 0xbfb8aa3b, v26
	v_mul_f32_e32 v27, 0xbfb8aa3b, v27
	v_exp_f32_e32 v28, v28
	v_exp_f32_e32 v29, v29
	v_exp_f32_e32 v30, v30
	v_exp_f32_e32 v31, v31
	v_exp_f32_e32 v24, v24
	v_exp_f32_e32 v25, v25
	v_exp_f32_e32 v26, v26
	v_exp_f32_e32 v27, v27
	v_add_f32_e32 v28, 1.0, v28
	v_add_f32_e32 v29, 1.0, v29
	v_add_f32_e32 v30, 1.0, v30
	v_add_f32_e32 v31, 1.0, v31
	v_add_f32_e32 v24, 1.0, v24
	v_add_f32_e32 v25, 1.0, v25
	v_add_f32_e32 v26, 1.0, v26
	v_add_f32_e32 v27, 1.0, v27
	v_rcp_f32_e32 v28, v28
	v_rcp_f32_e32 v29, v29
	v_rcp_f32_e32 v30, v30
	v_rcp_f32_e32 v31, v31
	v_rcp_f32_e32 v24, v24
	v_rcp_f32_e32 v25, v25
	v_rcp_f32_e32 v26, v26
	v_rcp_f32_e32 v27, v27
	v_lshlrev_b32_e32 v144, 16, v192
	v_and_b32_e32 v145, 0xffff0000, v192
	v_lshlrev_b32_e32 v242, 16, v196
	v_and_b32_e32 v243, 0xffff0000, v196
	v_lshlrev_b32_e32 v146, 16, v193
	v_and_b32_e32 v147, 0xffff0000, v193
	v_lshlrev_b32_e32 v244, 16, v197
	v_and_b32_e32 v245, 0xffff0000, v197
	v_lshlrev_b32_e32 v148, 16, v194
	v_and_b32_e32 v149, 0xffff0000, v194
	v_lshlrev_b32_e32 v246, 16, v198
	v_and_b32_e32 v247, 0xffff0000, v198
	v_lshlrev_b32_e32 v150, 16, v195
	v_and_b32_e32 v151, 0xffff0000, v195
	v_lshlrev_b32_e32 v248, 16, v199
	v_and_b32_e32 v249, 0xffff0000, v199
	v_pk_fma_f32 v[28:29], v[28:29], v[242:243], v[144:145]
	v_pk_fma_f32 v[30:31], v[30:31], v[244:245], v[146:147]
	v_pk_fma_f32 v[24:25], v[24:25], v[246:247], v[148:149]
	v_pk_fma_f32 v[26:27], v[26:27], v[248:249], v[150:151]
	global_store_dwordx4 v[224:225], v[28:31], off nt
	global_store_dwordx4 v[224:225], v[24:27], off offset:16 nt
	v_pk_mul_f32 v[20:21], v[20:21], v[238:239] op_sel_hi:[1,0]
	v_pk_mul_f32 v[22:23], v[22:23], v[238:239] op_sel_hi:[1,0]
	v_pk_mul_f32 v[16:17], v[16:17], v[238:239] op_sel_hi:[1,0]
	v_pk_mul_f32 v[18:19], v[18:19], v[238:239] op_sel_hi:[1,0]
	v_mul_f32_e32 v20, 0xbfb8aa3b, v20
	v_mul_f32_e32 v21, 0xbfb8aa3b, v21
	v_mul_f32_e32 v22, 0xbfb8aa3b, v22
	v_mul_f32_e32 v23, 0xbfb8aa3b, v23
	v_mul_f32_e32 v16, 0xbfb8aa3b, v16
	v_mul_f32_e32 v17, 0xbfb8aa3b, v17
	v_mul_f32_e32 v18, 0xbfb8aa3b, v18
	v_mul_f32_e32 v19, 0xbfb8aa3b, v19
	v_exp_f32_e32 v20, v20
	v_exp_f32_e32 v21, v21
	v_exp_f32_e32 v22, v22
	v_exp_f32_e32 v23, v23
	v_exp_f32_e32 v16, v16
	v_exp_f32_e32 v17, v17
	v_exp_f32_e32 v18, v18
	v_exp_f32_e32 v19, v19
	v_add_f32_e32 v20, 1.0, v20
	v_add_f32_e32 v21, 1.0, v21
	v_add_f32_e32 v22, 1.0, v22
	v_add_f32_e32 v23, 1.0, v23
	v_add_f32_e32 v16, 1.0, v16
	v_add_f32_e32 v17, 1.0, v17
	v_add_f32_e32 v18, 1.0, v18
	v_add_f32_e32 v19, 1.0, v19
	v_rcp_f32_e32 v20, v20
	v_rcp_f32_e32 v21, v21
	v_rcp_f32_e32 v22, v22
	v_rcp_f32_e32 v23, v23
	v_rcp_f32_e32 v16, v16
	v_rcp_f32_e32 v17, v17
	v_rcp_f32_e32 v18, v18
	v_rcp_f32_e32 v19, v19
	v_lshlrev_b32_e32 v144, 16, v200
	v_and_b32_e32 v145, 0xffff0000, v200
	v_lshlrev_b32_e32 v242, 16, v204
	v_and_b32_e32 v243, 0xffff0000, v204
	v_lshlrev_b32_e32 v146, 16, v201
	v_and_b32_e32 v147, 0xffff0000, v201
	v_lshlrev_b32_e32 v244, 16, v205
	v_and_b32_e32 v245, 0xffff0000, v205
	v_lshlrev_b32_e32 v148, 16, v202
	v_and_b32_e32 v149, 0xffff0000, v202
	v_lshlrev_b32_e32 v246, 16, v206
	v_and_b32_e32 v247, 0xffff0000, v206
	v_lshlrev_b32_e32 v150, 16, v203
	v_and_b32_e32 v151, 0xffff0000, v203
	v_lshlrev_b32_e32 v248, 16, v207
	v_and_b32_e32 v249, 0xffff0000, v207
	v_pk_fma_f32 v[20:21], v[20:21], v[242:243], v[144:145]
	v_pk_fma_f32 v[22:23], v[22:23], v[244:245], v[146:147]
	v_pk_fma_f32 v[16:17], v[16:17], v[246:247], v[148:149]
	v_pk_fma_f32 v[18:19], v[18:19], v[248:249], v[150:151]
	global_store_dwordx4 v[224:225], v[20:23], off offset:512 nt
	global_store_dwordx4 v[224:225], v[16:19], off offset:528 nt
	v_lshl_add_u64 v[224:225], v[224:225], 0, s[50:51]
	s_waitcnt vmcnt(12)
	v_pk_mul_f32 v[12:13], v[12:13], v[240:241] op_sel_hi:[1,0]
	v_pk_mul_f32 v[14:15], v[14:15], v[240:241] op_sel_hi:[1,0]
	v_pk_mul_f32 v[8:9], v[8:9], v[240:241] op_sel_hi:[1,0]
	v_pk_mul_f32 v[10:11], v[10:11], v[240:241] op_sel_hi:[1,0]
	v_mul_f32_e32 v12, 0xbfb8aa3b, v12
	v_mul_f32_e32 v13, 0xbfb8aa3b, v13
	v_mul_f32_e32 v14, 0xbfb8aa3b, v14
	v_mul_f32_e32 v15, 0xbfb8aa3b, v15
	v_mul_f32_e32 v8, 0xbfb8aa3b, v8
	v_mul_f32_e32 v9, 0xbfb8aa3b, v9
	v_mul_f32_e32 v10, 0xbfb8aa3b, v10
	v_mul_f32_e32 v11, 0xbfb8aa3b, v11
	v_exp_f32_e32 v12, v12
	v_exp_f32_e32 v13, v13
	v_exp_f32_e32 v14, v14
	v_exp_f32_e32 v15, v15
	v_exp_f32_e32 v8, v8
	v_exp_f32_e32 v9, v9
	v_exp_f32_e32 v10, v10
	v_exp_f32_e32 v11, v11
	v_add_f32_e32 v12, 1.0, v12
	v_add_f32_e32 v13, 1.0, v13
	v_add_f32_e32 v14, 1.0, v14
	v_add_f32_e32 v15, 1.0, v15
	v_add_f32_e32 v8, 1.0, v8
	v_add_f32_e32 v9, 1.0, v9
	v_add_f32_e32 v10, 1.0, v10
	v_add_f32_e32 v11, 1.0, v11
	v_rcp_f32_e32 v12, v12
	v_rcp_f32_e32 v13, v13
	v_rcp_f32_e32 v14, v14
	v_rcp_f32_e32 v15, v15
	v_rcp_f32_e32 v8, v8
	v_rcp_f32_e32 v9, v9
	v_rcp_f32_e32 v10, v10
	v_rcp_f32_e32 v11, v11
	v_lshlrev_b32_e32 v144, 16, v208
	v_and_b32_e32 v145, 0xffff0000, v208
	v_lshlrev_b32_e32 v242, 16, v212
	v_and_b32_e32 v243, 0xffff0000, v212
	v_lshlrev_b32_e32 v146, 16, v209
	v_and_b32_e32 v147, 0xffff0000, v209
	v_lshlrev_b32_e32 v244, 16, v213
	v_and_b32_e32 v245, 0xffff0000, v213
	v_lshlrev_b32_e32 v148, 16, v210
	v_and_b32_e32 v149, 0xffff0000, v210
	v_lshlrev_b32_e32 v246, 16, v214
	v_and_b32_e32 v247, 0xffff0000, v214
	v_lshlrev_b32_e32 v150, 16, v211
	v_and_b32_e32 v151, 0xffff0000, v211
	v_lshlrev_b32_e32 v248, 16, v215
	v_and_b32_e32 v249, 0xffff0000, v215
	v_pk_fma_f32 v[12:13], v[12:13], v[242:243], v[144:145]
	v_pk_fma_f32 v[14:15], v[14:15], v[244:245], v[146:147]
	v_pk_fma_f32 v[8:9], v[8:9], v[246:247], v[148:149]
	v_pk_fma_f32 v[10:11], v[10:11], v[248:249], v[150:151]
	global_store_dwordx4 v[224:225], v[12:15], off nt
	global_store_dwordx4 v[224:225], v[8:11], off offset:16 nt
	v_pk_mul_f32 v[4:5], v[4:5], v[240:241] op_sel_hi:[1,0]
	v_pk_mul_f32 v[6:7], v[6:7], v[240:241] op_sel_hi:[1,0]
	v_pk_mul_f32 v[0:1], v[0:1], v[240:241] op_sel_hi:[1,0]
	v_pk_mul_f32 v[2:3], v[2:3], v[240:241] op_sel_hi:[1,0]
	v_mul_f32_e32 v4, 0xbfb8aa3b, v4
	v_mul_f32_e32 v5, 0xbfb8aa3b, v5
	v_mul_f32_e32 v6, 0xbfb8aa3b, v6
	v_mul_f32_e32 v7, 0xbfb8aa3b, v7
	v_mul_f32_e32 v0, 0xbfb8aa3b, v0
	v_mul_f32_e32 v1, 0xbfb8aa3b, v1
	v_mul_f32_e32 v2, 0xbfb8aa3b, v2
	v_mul_f32_e32 v3, 0xbfb8aa3b, v3
	v_exp_f32_e32 v4, v4
	v_exp_f32_e32 v5, v5
	v_exp_f32_e32 v6, v6
	v_exp_f32_e32 v7, v7
	v_exp_f32_e32 v0, v0
	v_exp_f32_e32 v1, v1
	v_exp_f32_e32 v2, v2
	v_exp_f32_e32 v3, v3
	v_add_f32_e32 v4, 1.0, v4
	v_add_f32_e32 v5, 1.0, v5
	v_add_f32_e32 v6, 1.0, v6
	v_add_f32_e32 v7, 1.0, v7
	v_add_f32_e32 v0, 1.0, v0
	v_add_f32_e32 v1, 1.0, v1
	v_add_f32_e32 v2, 1.0, v2
	v_add_f32_e32 v3, 1.0, v3
	v_rcp_f32_e32 v4, v4
	v_rcp_f32_e32 v5, v5
	v_rcp_f32_e32 v6, v6
	v_rcp_f32_e32 v7, v7
	v_rcp_f32_e32 v0, v0
	v_rcp_f32_e32 v1, v1
	v_rcp_f32_e32 v2, v2
	v_rcp_f32_e32 v3, v3
	v_lshlrev_b32_e32 v144, 16, v216
	v_and_b32_e32 v145, 0xffff0000, v216
	v_lshlrev_b32_e32 v242, 16, v220
	v_and_b32_e32 v243, 0xffff0000, v220
	v_lshlrev_b32_e32 v146, 16, v217
	v_and_b32_e32 v147, 0xffff0000, v217
	v_lshlrev_b32_e32 v244, 16, v221
	v_and_b32_e32 v245, 0xffff0000, v221
	v_lshlrev_b32_e32 v148, 16, v218
	v_and_b32_e32 v149, 0xffff0000, v218
	v_lshlrev_b32_e32 v246, 16, v222
	v_and_b32_e32 v247, 0xffff0000, v222
	v_lshlrev_b32_e32 v150, 16, v219
	v_and_b32_e32 v151, 0xffff0000, v219
	v_lshlrev_b32_e32 v248, 16, v223
	v_and_b32_e32 v249, 0xffff0000, v223
	v_pk_fma_f32 v[4:5], v[4:5], v[242:243], v[144:145]
	v_pk_fma_f32 v[6:7], v[6:7], v[244:245], v[146:147]
	v_pk_fma_f32 v[0:1], v[0:1], v[246:247], v[148:149]
	v_pk_fma_f32 v[2:3], v[2:3], v[248:249], v[150:151]
	global_store_dwordx4 v[224:225], v[4:7], off offset:512 nt
	global_store_dwordx4 v[224:225], v[0:3], off offset:528 nt
	v_add_f32_e32 v112, v112, v113
	v_add_f32_e32 v116, v116, v117
	v_add_f32_e32 v120, v120, v121
	v_add_f32_e32 v124, v124, v125
	v_add_f32_e32 v96, v96, v97
	v_add_f32_e32 v100, v100, v101
	v_add_f32_e32 v104, v104, v105
	v_add_f32_e32 v108, v108, v109
	v_add_f32_e32 v114, v114, v115
	v_add_f32_e32 v118, v118, v119
	v_add_f32_e32 v122, v122, v123
	v_add_f32_e32 v126, v126, v127
	v_add_f32_e32 v98, v98, v99
	v_add_f32_e32 v102, v102, v103
	v_add_f32_e32 v106, v106, v107
	v_add_f32_e32 v110, v110, v111
	v_add_f32_e32 v112, v112, v114
	v_add_f32_e32 v116, v116, v118
	v_add_f32_e32 v120, v120, v122
	v_add_f32_e32 v124, v124, v126
	v_add_f32_e32 v96, v96, v98
	v_add_f32_e32 v100, v100, v102
	v_add_f32_e32 v104, v104, v106
	v_add_f32_e32 v108, v108, v110
	v_mov_b32_e32 v113, v112
	v_mov_b32_e32 v117, v116
	v_mov_b32_e32 v121, v120
	v_mov_b32_e32 v125, v124
	v_mov_b32_e32 v97, v96
	v_mov_b32_e32 v101, v100
	v_mov_b32_e32 v105, v104
	v_mov_b32_e32 v109, v108
	v_permlane16_swap_b32_e32 v113, v112
	v_permlane16_swap_b32_e32 v117, v116
	v_permlane16_swap_b32_e32 v121, v120
	v_permlane16_swap_b32_e32 v125, v124
	v_permlane16_swap_b32_e32 v97, v96
	v_permlane16_swap_b32_e32 v101, v100
	v_permlane16_swap_b32_e32 v105, v104
	v_permlane16_swap_b32_e32 v109, v108
	v_add_f32_e32 v112, v112, v113
	v_add_f32_e32 v116, v116, v117
	v_add_f32_e32 v120, v120, v121
	v_add_f32_e32 v124, v124, v125
	v_add_f32_e32 v96, v96, v97
	v_add_f32_e32 v100, v100, v101
	v_add_f32_e32 v104, v104, v105
	v_add_f32_e32 v108, v108, v109
	v_mov_b32_e32 v113, v112
	v_mov_b32_e32 v117, v116
	v_mov_b32_e32 v121, v120
	v_mov_b32_e32 v125, v124
	v_mov_b32_e32 v97, v96
	v_mov_b32_e32 v101, v100
	v_mov_b32_e32 v105, v104
	v_mov_b32_e32 v109, v108
	v_permlane32_swap_b32_e32 v113, v112
	v_permlane32_swap_b32_e32 v117, v116
	v_permlane32_swap_b32_e32 v121, v120
	v_permlane32_swap_b32_e32 v125, v124
	v_permlane32_swap_b32_e32 v97, v96
	v_permlane32_swap_b32_e32 v101, v100
	v_permlane32_swap_b32_e32 v105, v104
	v_permlane32_swap_b32_e32 v109, v108
	v_add_f32_e32 v112, v112, v113
	v_add_f32_e32 v116, v116, v117
	v_add_f32_e32 v120, v120, v121
	v_add_f32_e32 v124, v124, v125
	v_add_f32_e32 v96, v96, v97
	v_add_f32_e32 v100, v100, v101
	v_add_f32_e32 v104, v104, v105
	v_add_f32_e32 v108, v108, v109
	v_fmamk_f32 v112, v112, 0x3a800000, v158
	v_fmamk_f32 v116, v116, 0x3a800000, v158
	v_fmamk_f32 v120, v120, 0x3a800000, v158
	v_fmamk_f32 v124, v124, 0x3a800000, v158
	v_fmamk_f32 v96, v96, 0x3a800000, v158
	v_fmamk_f32 v100, v100, 0x3a800000, v158
	v_fmamk_f32 v104, v104, 0x3a800000, v158
	v_fmamk_f32 v108, v108, 0x3a800000, v158
	v_rsq_f32_e32 v226, v112
	v_rsq_f32_e32 v228, v116
	v_rsq_f32_e32 v230, v120
	v_rsq_f32_e32 v232, v124
	v_rsq_f32_e32 v234, v96
	v_rsq_f32_e32 v236, v100
	v_rsq_f32_e32 v238, v104
	v_rsq_f32_e32 v240, v108
	s_andn2_b64 vcc, exec, s[0:1]
	s_mov_b64 s[0:1], -1
	s_cbranch_vccnz .LBB0_1010
	s_andn2_b64 vcc, exec, s[4:5]
	s_cbranch_vccnz .LBB0_1009
	s_barrier
	s_branch .LBB0_1009
